# diff-attention tile loops: K/V prefetch uses saddr+voffset loads; 2 v_mad_u64_u32 + 2 v_lshl_add_u64 per tile replaced by SALU base math
# speedup vs baseline: 1.0016x; 1.0016x over previous
; #define GLOAD(K0, K1, V0, V1, kvt) do { const size_t ko_ = (size_t)(kvt) * 64 * QKVW; const int vo_ = (kvt) * 64; \
;         K0 = *(const u32x4*)(kg0 + ko_); K1 = *(const u32x4*)(kg1 + ko_); V0 = *(const u32x4*)(vg0 + vo_); V1 = *(const u32x4*)(vg1 + vo_); } while (0)
; #define STEP_LEAD(kvt, kslot, vso) do { f32x16 p0, p1; bool act, lval; \
;             QK_TILE(kvt, kslot); \
;             if (act) { SOFTMAX_HALF(p0, pa0, pb0); PV_HALF(vso, 0, pa0, pb0); SOFTMAX_HALF(p1, pa1, pb1); PV_HALF(vso, 2, pa1, pb1); } \
;         } while (0)
; #define STEP_TRAIL(kvt, kslot, vso) do { f32x16 p0, p1; bool act, lval; \
;             if (actp) { PV_HALF(vsp, 0, pa0, pb0); PV_HALF(vsp, 2, pa1, pb1); } \
;             QK_TILE(kvt, kslot); \
;             if (act) { SOFTMAX_FULL(p0, p1, pa0, pb0, pa1, pb1); } \
;             actp = act; vsp = (vso); \
;         } while (0)
; template <int MODE> ...
;     ...
;     { const bf16_t* qp = QKV + (tokbase + qpos) * QKVW + qcol + hi * 8;
; #pragma unroll
;       for (int dk = 0; dk < NDK; ++dk) qf[dk] = *(const bf16x8*)(qp + dk * 16); }
;     float m = NEG, l = 0.f;
;     f32x16 o[4];
; #pragma unroll
;     for (int i = 0; i < 4; ++i)
; #pragma unroll
;         for (int r = 0; r < 16; ++r) o[i][r] = 0.f;
;     u32x4 kr0, kr1, vr0, vr1;
;     const int idA = tid, idB = tid + 512;
;     const bf16_t* kg0 = QKV + (tokbase + (idA >> 4)) * QKVW + kcol + (idA & 15) * 8;
;     const bf16_t* kg1 = QKV + (tokbase + (idB >> 4)) * QKVW + kcol + (idB & 15) * 8;
;     const bf16_t* vg0 = VTb + (size_t)(idA >> 3) * SEQ + (idA & 7) * 8;
;     const bf16_t* vg1 = VTb + (size_t)(idB >> 3) * SEQ + (idB & 7) * 8;
;     const int kl0 = (idA >> 4) * KP + (idA & 15) * 16, kl1 = (idB >> 4) * KP + (idB & 15) * 16;
;     const int vl0 = VRING + (idA >> 3) * VP + ((idA & 7) >> 1) * 32 + (idA & 1) * 8, vl1 = VRING + (idB >> 3) * VP + ((idB & 7) >> 1) * 32 + (idB & 1) * 8;
;     ...
;     GLOAD(kr0, kr1, vr0, vr1, TILE_AT(0));
;     if (trailing) {
;         TILE_LOOP(STEP_TRAIL);
;         if (actp) { PV_HALF(vsp, 0, pa0, pb0); PV_HALF(vsp, 2, pa1, pb1); }
;     } else {
;         TILE_LOOP(STEP_LEAD);
.LBB0_264:
	v_mov_b32_e32 v14, v202
	s_lshl_b32 s28, s29, 7
	v_readfirstlane_b32 s4, v14
	s_ashr_i32 s79, s4, 2
	s_andn2_b32 s79, s79, 31
	v_and_b32_e32 v167, 31, v14
	s_add_i32 s80, s79, s28
	s_ashr_i32 s54, s4, 6
	s_waitcnt vmcnt(16)
	v_or_b32_e32 v146, s80, v167
	s_and_b32 s78, s54, 1
	v_ashrrev_i32_e32 v147, 31, v146
	s_lshl_b32 s55, s78, 6
	v_lshl_add_u64 v[144:145], s[14:15], 0, v[146:147]
	v_mov_b64_e32 v[0:1], s[68:69]
	s_or_b32 s24, s55, s1
	v_mad_u64_u32 v[0:1], s[4:5], v144, s35, v[0:1]
	v_bfe_u32 v64, v14, 5, 1
	v_mad_i32_i24 v1, v145, s35, v1
	s_lshl_b32 s24, s24, 1
	v_lshl_add_u64 v[0:1], v[0:1], 0, s[24:25]
	v_lshlrev_b32_e32 v160, 4, v64
	v_lshl_add_u64 v[0:1], v[0:1], 0, v[160:161]
	global_load_dwordx4 v[96:99], v[0:1], off
	global_load_dwordx4 v[100:103], v[0:1], off offset:32
	global_load_dwordx4 v[104:107], v[0:1], off offset:64
	global_load_dwordx4 v[108:111], v[0:1], off offset:96
	v_ashrrev_i32_e32 v0, 4, v14
	v_ashrrev_i32_e32 v1, 31, v0
	v_lshl_add_u64 v[2:3], s[14:15], 0, v[0:1]
	v_mov_b64_e32 v[4:5], s[44:45]
	v_mad_u64_u32 v[6:7], s[4:5], v2, s35, v[4:5]
	v_lshlrev_b32_e32 v1, 4, v14
	v_add_u32_e32 v12, 0x200, v14
	v_mad_i32_i24 v7, v3, s35, v7
	v_and_b32_e32 v2, 0xf0, v1
	v_mov_b32_e32 v3, v161
	v_lshl_add_u64 v[148:149], v[6:7], 0, v[2:3]
	v_ashrrev_i32_e32 v6, 4, v12
	v_ashrrev_i32_e32 v7, 31, v6
	v_lshl_add_u64 v[8:9], s[14:15], 0, v[6:7]
	v_mad_u64_u32 v[4:5], s[4:5], v8, s35, v[4:5]
	v_mad_i32_i24 v5, v9, s35, v5
	v_lshl_add_u64 v[150:151], v[4:5], 0, v[2:3]
	v_ashrrev_i32_e32 v4, 3, v14
	v_ashrrev_i32_e32 v5, 31, v4
	v_lshlrev_b64 v[8:9], 13, v[4:5]
	v_and_b32_e32 v3, 7, v14
	v_lshl_add_u64 v[8:9], s[42:43], 0, v[8:9]
	v_lshlrev_b32_e32 v10, 4, v3
	v_mov_b32_e32 v11, v161
	v_lshl_add_u64 v[152:153], v[8:9], 0, v[10:11]
	v_ashrrev_i32_e32 v8, 3, v12
	v_ashrrev_i32_e32 v9, 31, v8
	v_lshlrev_b64 v[12:13], 13, v[8:9]
	v_lshl_add_u64 v[12:13], s[42:43], 0, v[12:13]
	v_lshl_add_u64 v[154:155], v[12:13], 0, v[10:11]
	global_load_dwordx4 v[116:119], v[148:149], off offset:2048
	global_load_dwordx4 v[120:123], v[150:151], off offset:2048
	global_load_dwordx4 v[124:127], v[152:153], off
	global_load_dwordx4 v[112:115], v[154:155], off
	v_subrev_u32_e32 v238, s44, v148
	v_subrev_u32_e32 v239, s44, v150
	v_subrev_u32_e32 v240, s42, v152
	v_subrev_u32_e32 v241, s42, v154
	v_lshlrev_b32_e32 v3, 3, v64
	v_mad_u64_u32 v[156:157], s[4:5], v0, s49, v[2:3]
	v_mad_u64_u32 v[158:159], s[4:5], v6, s49, v[2:3]
	v_lshlrev_b32_e32 v2, 3, v14
	s_lshl_b32 s24, s29, 1
	v_and_b32_e32 v1, 0x60, v1
	v_and_b32_e32 v2, 8, v2
	s_add_i32 s81, s24, 2
	v_mul_lo_u32 v0, v4, s23
	v_mul_lo_u32 v4, v8, s23
	v_or_b32_e32 v5, v1, v2
	s_or_b32 s86, s24, 1
	v_or_b32_e32 v3, s55, v3
	s_cmp_gt_i32 s54, 3
	s_mov_b64 s[4:5], -1
	v_mul_u32_u24_e32 v159, 0x110, v167
	v_mul_u32_u24_e32 v157, 0x90, v167
	v_add3_u32 v169, v0, v2, v1
	v_add_u32_e32 v170, v5, v4
	v_lshlrev_b32_e32 v171, 1, v3
	v_lshlrev_b32_e32 v147, 2, v64
	s_cbranch_scc1 .LBB0_278
	v_mov_b32_e32 v14, v161
	v_mov_b32_e32 v15, v161
	v_mov_b32_e32 v0, v161
	v_mov_b32_e32 v1, v161
	v_mov_b32_e32 v2, v161
	v_mov_b32_e32 v3, v161
	v_mov_b32_e32 v4, v161
	v_mov_b32_e32 v5, v161
	v_mov_b32_e32 v6, v161
	v_mov_b32_e32 v7, v161
	v_mov_b32_e32 v8, v161
	v_mov_b32_e32 v9, v161
	v_mov_b32_e32 v10, v161
	v_mov_b32_e32 v11, v161
	v_mov_b32_e32 v12, v161
	v_mov_b32_e32 v13, v161
	v_mov_b64_e32 v[30:31], v[14:15]
	v_mov_b64_e32 v[46:47], v[14:15]
	v_mov_b64_e32 v[62:63], v[14:15]
	s_waitcnt vmcnt(3)
	v_mov_b64_e32 v[134:135], v[118:119]
	s_waitcnt vmcnt(2)
	v_mov_b64_e32 v[138:139], v[122:123]
	s_waitcnt vmcnt(1)
	v_mov_b64_e32 v[142:143], v[126:127]
	s_waitcnt vmcnt(0)
	v_mov_b64_e32 v[130:131], v[114:115]
	s_or_b32 s4, s80, 31
	s_mov_b32 s5, 1
	v_lshlrev_b32_e32 v166, 2, v64
	s_add_i32 s29, s28, 0x80
	s_mov_b32 s54, 0
	v_mov_b32_e32 v172, 0
	v_mov_b32_e32 v173, 0xf149f2ca
	v_mov_b64_e32 v[28:29], v[12:13]
	v_mov_b64_e32 v[26:27], v[10:11]
	v_mov_b64_e32 v[24:25], v[8:9]
	v_mov_b64_e32 v[22:23], v[6:7]
	v_mov_b64_e32 v[20:21], v[4:5]
	v_mov_b64_e32 v[18:19], v[2:3]
	v_mov_b64_e32 v[16:17], v[0:1]
	v_mov_b64_e32 v[44:45], v[12:13]
	v_mov_b64_e32 v[42:43], v[10:11]
	v_mov_b64_e32 v[40:41], v[8:9]
	v_mov_b64_e32 v[38:39], v[6:7]
	v_mov_b64_e32 v[36:37], v[4:5]
	v_mov_b64_e32 v[34:35], v[2:3]
	v_mov_b64_e32 v[32:33], v[0:1]
	v_mov_b64_e32 v[60:61], v[12:13]
	v_mov_b64_e32 v[58:59], v[10:11]
	v_mov_b64_e32 v[56:57], v[8:9]
	v_mov_b64_e32 v[54:55], v[6:7]
	v_mov_b64_e32 v[52:53], v[4:5]
	v_mov_b64_e32 v[50:51], v[2:3]
	v_mov_b64_e32 v[48:49], v[0:1]
	v_mov_b64_e32 v[132:133], v[116:117]
	v_mov_b64_e32 v[136:137], v[120:121]
	v_mov_b64_e32 v[140:141], v[124:125]
	v_mov_b64_e32 v[128:129], v[112:113]
	s_mov_b32 s55, 0
	s_mov_b32 s87, 0
	s_branch .LBB0_269

.LBB0_269:
	s_add_i32 s89, s55, 0
	v_add_u32_e32 v64, s89, v156
	s_add_i32 s88, s87, 0
	s_waitcnt vmcnt(3)
	ds_write_b128 v64, v[132:135]
	v_add_u32_e32 v64, s89, v158
	s_waitcnt vmcnt(2)
	ds_write_b128 v64, v[136:139]
	v_add_u32_e32 v64, s88, v169
	v_add_u32_e32 v64, 0x8800, v64
	s_waitcnt vmcnt(1)
	ds_write2_b64 v64, v[140:141], v[142:143] offset1:2
	v_add_u32_e32 v64, s88, v170
	s_cmp_lt_u32 s5, s81
	v_add_u32_e32 v64, 0x8800, v64
	s_cselect_b32 s92, s5, s86
	s_waitcnt vmcnt(0)
	ds_write2_b64 v64, v[128:129], v[130:131] offset1:2
	s_lshl_b32 s24, s92, 7
	s_mul_i32 s90, s92, 0xc0000
	s_add_u32 s90, s44, s90
	s_addc_u32 s91, s45, 0
	s_add_u32 s98, s42, s24
	s_addc_u32 s99, s43, 0
	s_waitcnt lgkmcnt(0)
	s_barrier
	global_load_dwordx4 v[132:135], v238, s[90:91] offset:2048
	global_load_dwordx4 v[136:139], v239, s[90:91] offset:2048
	global_load_dwordx4 v[140:143], v240, s[98:99]
	global_load_dwordx4 v[128:131], v241, s[98:99]
	s_cmp_gt_i32 s54, s4
	s_cbranch_scc1 .LBB0_268
	v_add3_u32 v76, s89, v159, v171
	ds_read_b128 v[64:67], v76
	ds_read_b128 v[68:71], v76 offset:32
	ds_read_b128 v[72:75], v76 offset:64
	ds_read_b128 v[174:177], v76 offset:96
	s_add_i32 s24, s54, 63
	s_cmp_le_i32 s24, s80
	s_waitcnt lgkmcnt(3)
	v_mfma_f32_32x32x16_bf16 v[80:95], v[64:67], v[96:99], 0
	s_waitcnt lgkmcnt(2)
	v_mfma_f32_32x32x16_bf16 v[80:95], v[68:71], v[100:103], v[80:95]
	ds_read_b128 v[64:67], v76 offset:8704
	ds_read_b128 v[178:181], v76 offset:8736
	ds_read_b128 v[186:189], v76 offset:8768
	ds_read_b128 v[190:193], v76 offset:8800
	s_waitcnt lgkmcnt(5)
	v_mfma_f32_32x32x16_bf16 v[80:95], v[72:75], v[104:107], v[80:95]
	s_waitcnt lgkmcnt(3)
	v_mfma_f32_32x32x16_bf16 v[64:79], v[64:67], v[96:99], 0
	s_waitcnt lgkmcnt(2)
	v_mfma_f32_32x32x16_bf16 v[64:79], v[178:181], v[100:103], v[64:79]
	s_waitcnt lgkmcnt(1)
	v_mfma_f32_32x32x16_bf16 v[64:79], v[186:189], v[104:107], v[64:79]
	s_waitcnt lgkmcnt(0)
	v_mfma_f32_32x32x16_bf16 v[64:79], v[190:193], v[108:111], v[64:79]
	v_mfma_f32_32x32x16_bf16 v[80:95], v[174:177], v[108:111], v[80:95]
	s_cbranch_scc1 .LBB0_272
	v_add_u32_e32 v168, s54, v166
	v_add_u32_e32 v174, 32, v168
	v_cmp_le_i32_e32 vcc, v174, v146
	v_add_u32_e32 v174, 33, v168
	s_nop 5
	v_cndmask_b32_e32 v64, v213, v64, vcc
	v_cmp_lt_i32_e32 vcc, v168, v146
	s_nop 1
	v_cndmask_b32_e32 v81, v213, v81, vcc
	v_cmp_le_i32_e32 vcc, v168, v146
	s_nop 1
	v_cndmask_b32_e32 v80, v213, v80, vcc
	v_cmp_le_i32_e32 vcc, v174, v146
	v_add_u32_e32 v174, 2, v168
	s_nop 0
	v_cndmask_b32_e32 v65, v213, v65, vcc
	v_cmp_le_i32_e32 vcc, v174, v146
	v_add_u32_e32 v174, 34, v168
	s_nop 0
	v_cndmask_b32_e32 v82, v213, v82, vcc
	v_cmp_le_i32_e32 vcc, v174, v146
	v_add_u32_e32 v174, 3, v168
	s_nop 0
	v_cndmask_b32_e32 v66, v213, v66, vcc
	v_cmp_le_i32_e32 vcc, v174, v146
	v_add_u32_e32 v174, 35, v168
	s_nop 0
	v_cndmask_b32_e32 v83, v213, v83, vcc
	v_cmp_le_i32_e32 vcc, v174, v146
	v_add_u32_e32 v174, 8, v168
	s_nop 0
	v_cndmask_b32_e32 v67, v213, v67, vcc
	v_cmp_le_i32_e32 vcc, v174, v146
	v_add_u32_e32 v174, 40, v168
	s_nop 0
	v_cndmask_b32_e32 v84, v213, v84, vcc
	v_cmp_le_i32_e32 vcc, v174, v146
	v_add_u32_e32 v174, 9, v168
	s_nop 0
	v_cndmask_b32_e32 v68, v213, v68, vcc
	v_cmp_le_i32_e32 vcc, v174, v146
	v_add_u32_e32 v174, 41, v168
	s_nop 0
	v_cndmask_b32_e32 v85, v213, v85, vcc
	v_cmp_le_i32_e32 vcc, v174, v146
	v_add_u32_e32 v174, 10, v168
	s_nop 0
	v_cndmask_b32_e32 v69, v213, v69, vcc
	v_cmp_le_i32_e32 vcc, v174, v146
	v_add_u32_e32 v174, 42, v168
	s_nop 0
	v_cndmask_b32_e32 v86, v213, v86, vcc
	v_cmp_le_i32_e32 vcc, v174, v146
	v_add_u32_e32 v174, 11, v168
	s_nop 0
	v_cndmask_b32_e32 v70, v213, v70, vcc
	v_cmp_le_i32_e32 vcc, v174, v146
	v_add_u32_e32 v174, 43, v168
	s_nop 0
	v_cndmask_b32_e32 v87, v213, v87, vcc
	v_cmp_le_i32_e32 vcc, v174, v146
	v_add_u32_e32 v174, 16, v168
	s_nop 0
	v_cndmask_b32_e32 v71, v213, v71, vcc
	v_cmp_le_i32_e32 vcc, v174, v146
	v_add_u32_e32 v174, 48, v168
	s_nop 0
	v_cndmask_b32_e32 v88, v213, v88, vcc
	v_cmp_le_i32_e32 vcc, v174, v146
	v_add_u32_e32 v174, 17, v168
	s_nop 0
	v_cndmask_b32_e32 v72, v213, v72, vcc
	v_cmp_le_i32_e32 vcc, v174, v146
	v_add_u32_e32 v174, 49, v168
	s_nop 0
	v_cndmask_b32_e32 v89, v213, v89, vcc
	v_cmp_le_i32_e32 vcc, v174, v146
	v_add_u32_e32 v174, 18, v168
	s_nop 0
	v_cndmask_b32_e32 v73, v213, v73, vcc
	v_cmp_le_i32_e32 vcc, v174, v146
	v_add_u32_e32 v174, 50, v168
	s_nop 0
	v_cndmask_b32_e32 v90, v213, v90, vcc
	v_cmp_le_i32_e32 vcc, v174, v146
	v_add_u32_e32 v174, 19, v168
	s_nop 0
	v_cndmask_b32_e32 v74, v213, v74, vcc
	v_cmp_le_i32_e32 vcc, v174, v146
	v_add_u32_e32 v174, 51, v168
	s_nop 0
	v_cndmask_b32_e32 v91, v213, v91, vcc
	v_cmp_le_i32_e32 vcc, v174, v146
	v_add_u32_e32 v174, 24, v168
	s_nop 0
	v_cndmask_b32_e32 v75, v213, v75, vcc
	v_cmp_le_i32_e32 vcc, v174, v146
	v_add_u32_e32 v174, 56, v168
	s_nop 0
	v_cndmask_b32_e32 v92, v213, v92, vcc
	v_cmp_le_i32_e32 vcc, v174, v146
	v_add_u32_e32 v174, 25, v168
	s_nop 0
	v_cndmask_b32_e32 v76, v213, v76, vcc
	v_cmp_le_i32_e32 vcc, v174, v146
	v_add_u32_e32 v174, 57, v168
	s_nop 0
	v_cndmask_b32_e32 v93, v213, v93, vcc
	v_cmp_le_i32_e32 vcc, v174, v146
	v_add_u32_e32 v174, 26, v168
	s_nop 0
	v_cndmask_b32_e32 v77, v213, v77, vcc
	v_cmp_le_i32_e32 vcc, v174, v146
	v_add_u32_e32 v174, 58, v168
	s_nop 0
	v_cndmask_b32_e32 v94, v213, v94, vcc
	v_cmp_le_i32_e32 vcc, v174, v146
	v_add_u32_e32 v174, 27, v168
	v_add_u32_e32 v168, 59, v168
	v_cndmask_b32_e32 v78, v213, v78, vcc
	v_cmp_le_i32_e32 vcc, v174, v146
	s_nop 1
	v_cndmask_b32_e32 v95, v213, v95, vcc
	v_cmp_le_i32_e32 vcc, v168, v146
	s_nop 1
	v_cndmask_b32_e32 v79, v213, v79, vcc

.LBB0_280:
	s_add_i32 s90, s88, 0
	v_add_u32_e32 v72, s90, v156
	s_add_i32 s89, s87, 0
	s_waitcnt vmcnt(3)
	ds_write_b128 v72, v[116:119]
	v_add_u32_e32 v72, s90, v158
	s_waitcnt vmcnt(2)
	ds_write_b128 v72, v[120:123]
	v_add_u32_e32 v72, s89, v169
	v_add_u32_e32 v72, 0x8800, v72
	s_waitcnt vmcnt(1)
	ds_write2_b64 v72, v[124:125], v[126:127] offset1:2
	v_add_u32_e32 v72, s89, v170
	s_cmp_lt_u32 s5, s81
	v_add_u32_e32 v72, 0x8800, v72
	s_cselect_b32 s94, s5, s86
	s_waitcnt vmcnt(0)
	ds_write2_b64 v72, v[112:113], v[114:115] offset1:2
	s_lshl_b32 s24, s94, 7
	s_mul_i32 s92, s94, 0xc0000
	s_add_u32 s92, s44, s92
	s_addc_u32 s93, s45, 0
	s_add_u32 s98, s42, s24
	s_addc_u32 s99, s43, 0
	s_waitcnt lgkmcnt(0)
	s_barrier
	global_load_dwordx4 v[116:119], v238, s[92:93] offset:2048
	global_load_dwordx4 v[120:123], v239, s[92:93] offset:2048
	global_load_dwordx4 v[124:127], v240, s[98:99]
	global_load_dwordx4 v[112:115], v241, s[98:99]
	s_andn2_b64 vcc, exec, s[54:55]
	s_cbranch_vccnz .LBB0_282
	v_add_u32_e32 v128, s91, v129
	ds_read_b128 v[72:75], v128 offset:34816
	ds_read_b128 v[76:79], v128 offset:34848
	ds_read_b128 v[88:91], v128 offset:39424
	ds_read_b128 v[92:95], v128 offset:39456
	s_waitcnt lgkmcnt(3)
	v_mfma_f32_32x32x16_bf16 v[48:63], v[72:75], v[80:83], v[48:63]
	s_waitcnt lgkmcnt(1)
	v_mfma_f32_32x32x16_bf16 v[32:47], v[88:91], v[80:83], v[32:47]
	v_mfma_f32_32x32x16_bf16 v[48:63], v[76:79], v[84:87], v[48:63]
	s_waitcnt lgkmcnt(0)
	v_mfma_f32_32x32x16_bf16 v[32:47], v[92:95], v[84:87], v[32:47]
	ds_read_b128 v[72:75], v128 offset:44032
	ds_read_b128 v[76:79], v128 offset:44064
	ds_read_b128 v[88:91], v128 offset:48640
	ds_read_b128 v[92:95], v128 offset:48672
	s_waitcnt lgkmcnt(3)
	v_mfma_f32_32x32x16_bf16 v[16:31], v[72:75], v[80:83], v[16:31]
	s_waitcnt lgkmcnt(1)
	v_mfma_f32_32x32x16_bf16 v[0:15], v[88:91], v[80:83], v[0:15]
	v_mfma_f32_32x32x16_bf16 v[16:31], v[76:79], v[84:87], v[16:31]
	s_waitcnt lgkmcnt(0)
	v_mfma_f32_32x32x16_bf16 v[0:15], v[92:95], v[84:87], v[0:15]
	ds_read_b128 v[72:75], v128 offset:34880
	ds_read_b128 v[76:79], v128 offset:34912
	ds_read_b128 v[88:91], v128 offset:39488
	ds_read_b128 v[92:95], v128 offset:39520
	s_waitcnt lgkmcnt(3)
	v_mfma_f32_32x32x16_bf16 v[48:63], v[72:75], v[64:67], v[48:63]
	s_waitcnt lgkmcnt(1)
	v_mfma_f32_32x32x16_bf16 v[32:47], v[88:91], v[64:67], v[32:47]
	v_mfma_f32_32x32x16_bf16 v[48:63], v[76:79], v[68:71], v[48:63]
	s_waitcnt lgkmcnt(0)
	v_mfma_f32_32x32x16_bf16 v[32:47], v[92:95], v[68:71], v[32:47]
	ds_read_b128 v[72:75], v128 offset:44096
	ds_read_b128 v[76:79], v128 offset:44128
	ds_read_b128 v[88:91], v128 offset:48704
	ds_read_b128 v[92:95], v128 offset:48736
	s_waitcnt lgkmcnt(3)
	v_mfma_f32_32x32x16_bf16 v[16:31], v[72:75], v[64:67], v[16:31]
	s_waitcnt lgkmcnt(1)
	v_mfma_f32_32x32x16_bf16 v[0:15], v[88:91], v[64:67], v[0:15]
	v_mfma_f32_32x32x16_bf16 v[16:31], v[76:79], v[68:71], v[16:31]
	s_waitcnt lgkmcnt(0)
	v_mfma_f32_32x32x16_bf16 v[0:15], v[92:95], v[68:71], v[0:15]
